# step order: FFN-in f2 runs before K/V projections (its repeated A reads leave the stream in the memory-side cache for the projections); V^T rounds reversed
# speedup vs baseline: 1.0032x; 1.0032x over previous
.LBB0_14:
	s_mov_b64 s[80:81], s[94:95]
	v_mov_b32_e32 v237, v190
	s_waitcnt lgkmcnt(0)
	s_load_dwordx2 s[78:79], s[80:81], 0x90
	s_load_dword s3, s[76:77], 0x0
	s_mov_b32 s72, s0
	s_and_b32 s47, s0, 7
	s_lshl_b32 s47, s47, 2
	s_mov_b32 s1, 0x96543210
	s_cmp_gt_u32 s0, 7
	s_cselect_b32 s1, 0xfedcba87, s1
	s_lshr_b32 s1, s1, s47
	s_and_b32 s47, s1, 15
	v_readfirstlane_b32 s74, v237
	v_and_b32_e32 v236, 63, v237
	s_mov_b64 s[6:7], -1
	s_mov_b64 s[48:49], 0
	s_cmp_lt_i32 s47, 8
	s_mov_b64 s[10:11], 0
	s_mov_b64 s[82:83], 0
	s_mov_b64 s[8:9], 0
	s_cbranch_scc1 .LBB0_64
	s_mov_b32 s73, s72
	s_mov_b32 s72, s86
	s_cmp_gt_i32 s47, 10
	s_cbranch_scc0 .LBB0_23
	s_mov_b64 s[8:9], -1
	s_mov_b64 s[86:87], 0
	s_cmp_gt_i32 s47, 11
	s_cbranch_scc0 .LBB0_24
	s_cmp_gt_i32 s47, 13
	s_cbranch_scc0 .LBB0_19
	s_cmp_eq_u32 s47, 14
	s_mov_b64 s[6:7], 0
	s_mov_b64 s[10:11], -1
	s_cselect_b64 s[82:83], -1, 0

.LBB0_356:
	s_add_i32 s0, s72, 1
	s_cmp_ge_i32 s0, s75
	s_cselect_b64 s[6:7], -1, 0
	s_cmp_lt_i32 s0, s75
	s_cselect_b64 s[8:9], -1, 0
	s_add_i32 s47, s47, -7
	s_andn2_b32 s47, s47, 2
	s_cmp_lg_u32 s47, 0
	s_cselect_b64 s[10:11], -1, 0
	s_and_b64 s[8:9], s[8:9], s[10:11]
	s_andn2_b64 vcc, exec, s[8:9]
	s_cbranch_vccnz .LBB0_13
	v_readlane_b32 s1, v254, 0
	s_cmp_lg_u32 s72, s1
	s_mov_b64 s[8:9], -1
	s_cbranch_scc0 .LBB0_411
	s_getreg_b32 s1, hwreg(HW_REG_XCC_ID, 0, 4)
	s_waitcnt vmcnt(0)
	s_waitcnt vmcnt(0) lgkmcnt(0)
	s_barrier
	s_mov_b64 s[8:9], exec
	v_readlane_b32 s10, v254, 24
	v_readlane_b32 s11, v254, 25
	s_and_b64 s[10:11], s[8:9], s[10:11]
	s_mov_b64 exec, s[10:11]
	s_cbranch_execz .LBB0_410
	s_add_i32 s4, 0, 0x21000
	v_mov_b32_e32 v0, s4
	s_waitcnt vmcnt(0) expcnt(0) lgkmcnt(0)
	ds_read_b32 v2, v0
	v_readlane_b32 s10, v254, 23
	s_and_b32 s1, s1, 15
	s_waitcnt lgkmcnt(0)
	v_cmp_ne_u32_e32 vcc, 0, v2
	v_mov_b32_e32 v0, s10
	ds_read_b32 v0, v0
	s_cbranch_vccnz .LBB0_374
	s_load_dwordx2 s[14:15], s[76:77], 0x4
	s_add_u32 s10, s78, 0x200200
	s_addc_u32 s11, s79, 0
	s_add_u32 s12, s78, 0x200400
	s_addc_u32 s13, s79, 0
	s_waitcnt lgkmcnt(0)
	s_mul_i32 s3, s14, s3
	s_add_u32 s14, s78, 0x200500
	s_mul_i32 s3, s3, s15
	s_addc_u32 s15, s79, 0
	s_add_u32 s16, s78, 0x200600
	s_addc_u32 s17, s79, 0
	s_add_u32 s18, s78, 0x200700
	s_addc_u32 s19, s79, 0
	s_add_u32 s20, s78, 0x200800
	s_addc_u32 s21, s79, 0
	s_add_u32 s22, s78, 0x200900
	s_addc_u32 s23, s79, 0
	s_add_u32 s24, s78, 0x200a00
	s_addc_u32 s25, s79, 0
	s_add_u32 s26, s78, 0x200b00
	s_addc_u32 s27, s79, 0
	s_add_u32 s28, s78, 0x200c00
	s_addc_u32 s29, s79, 0
	s_add_u32 s30, s78, 0x200d00
	s_addc_u32 s31, s79, 0
	s_add_u32 s34, s78, 0x200e00
	s_addc_u32 s35, s79, 0
	s_add_u32 s36, s78, 0x200f00
	s_addc_u32 s37, s79, 0
	s_add_u32 s38, s78, 0x201000
	s_addc_u32 s39, s79, 0
	s_add_u32 s40, s78, 0x201100
	s_addc_u32 s41, s79, 0
	s_add_u32 s52, s78, 0x201200
	s_addc_u32 s53, s79, 0
	s_add_u32 s80, s78, 0x201300
	s_addc_u32 s81, s79, 0
	s_mov_b32 s33, 1
	s_branch .LBB0_362
